# baseline (speedup 1.0000x reference)
.LBB0_562:
	v_ashrrev_i32_e32 v69, 31, v68
	v_mov_b64_e32 v[0:1], s[96:97]
	v_add_u32_e32 v98, 0x9000, v68
	v_mad_i64_i32 v[92:93], s[0:1], v68, s43, v[0:1]
	v_mov_b32_e32 v89, v96
	v_lshlrev_b64 v[0:1], 10, v[68:69]
	v_ashrrev_i32_e32 v99, 31, v98
	v_lshl_add_u64 v[90:91], v[92:93], 0, v[88:89]
	v_lshl_add_u64 v[6:7], v[70:71], 0, v[0:1]
	v_lshlrev_b64 v[10:11], 10, v[98:99]
	global_load_dwordx4 v[2:5], v[90:91], off offset:3072
	v_lshl_add_u64 v[10:11], v[70:71], 0, v[10:11]
	global_load_dwordx4 v[6:9], v[6:7], off
	v_lshl_add_u64 v[0:1], v[72:73], 0, v[0:1]
	global_load_dwordx4 v[100:103], v[10:11], off
	v_cmp_lt_i32_e32 vcc, s42, v68
	v_mov_b32_e32 v111, 0
	s_waitcnt vmcnt(2)
	v_lshlrev_b32_e32 v10, 16, v2
	v_and_b32_e32 v11, 0xffff0000, v2
	s_waitcnt vmcnt(1)
	v_lshlrev_b32_e32 v94, 16, v6
	v_and_b32_e32 v95, 0xffff0000, v6
	v_lshlrev_b32_e32 v2, 16, v3
	v_and_b32_e32 v3, 0xffff0000, v3
	v_lshlrev_b32_e32 v6, 16, v7
	v_and_b32_e32 v7, 0xffff0000, v7
	s_waitcnt vmcnt(0)
	v_lshlrev_b32_e32 v108, 16, v100
	v_and_b32_e32 v109, 0xffff0000, v100
	v_pk_fma_f32 v[10:11], v[12:13], v[10:11], v[94:95]
	v_lshlrev_b32_e32 v94, 16, v101
	v_and_b32_e32 v95, 0xffff0000, v101
	v_pk_fma_f32 v[2:3], v[26:27], v[2:3], v[6:7]
	v_pk_add_f32 v[10:11], v[10:11], v[108:109]
	v_lshlrev_b32_e32 v104, 16, v4
	v_and_b32_e32 v105, 0xffff0000, v4
	v_lshlrev_b32_e32 v106, 16, v8
	v_and_b32_e32 v107, 0xffff0000, v8
	v_lshlrev_b32_e32 v6, 16, v102
	v_and_b32_e32 v7, 0xffff0000, v102
	v_pk_add_f32 v[2:3], v[2:3], v[94:95]
	v_mul_f32_e32 v89, 0x3d372713, v10
	v_mul_f32_e32 v102, 0x3d372713, v11
	v_pk_fma_f32 v[100:101], v[40:41], v[104:105], v[106:107]
	v_mul_f32_e32 v106, 0x3d372713, v2
	v_mul_f32_e32 v107, 0x3d372713, v3
	v_mul_f32_e32 v89, v10, v89
	v_mul_f32_e32 v102, v11, v102
	v_pk_mul_f32 v[94:95], v[10:11], 0.5 op_sel_hi:[1,0]
	v_mul_f32_e32 v106, v2, v106
	v_mul_f32_e32 v107, v3, v107
	v_fma_f32 v10, v10, v89, v10
	v_fmac_f32_e32 v11, v11, v102
	v_pk_add_f32 v[6:7], v[100:101], v[6:7]
	v_pk_mul_f32 v[100:101], v[2:3], 0.5 op_sel_hi:[1,0]
	v_fma_f32 v2, v2, v106, v2
	v_fmac_f32_e32 v3, v3, v107
	v_mul_f32_e32 v10, 0x3f4c422a, v10
	v_mul_f32_e32 v11, 0x3f4c422a, v11
	v_mul_f32_e32 v109, 0x3d372713, v7
	v_mul_f32_e32 v2, 0x3f4c422a, v2
	v_mul_f32_e32 v3, 0x3f4c422a, v3
	v_add_f32_e32 v10, v10, v10
	v_add_f32_e32 v11, v11, v11
	v_mul_f32_e32 v109, v7, v109
	v_add_f32_e32 v2, v2, v2
	v_add_f32_e32 v3, v3, v3
	v_mul_f32_e32 v10, 0x3fb8aa3b, v10
	v_mul_f32_e32 v11, 0x3fb8aa3b, v11
	v_pk_mul_f32 v[104:105], v[6:7], 0.5 op_sel_hi:[1,0]
	v_fmac_f32_e32 v7, v7, v109
	v_mul_f32_e32 v2, 0x3fb8aa3b, v2
	v_mul_f32_e32 v3, 0x3fb8aa3b, v3
	v_exp_f32_e32 v10, v10
	v_exp_f32_e32 v11, v11
	v_mul_f32_e32 v7, 0x3f4c422a, v7
	v_exp_f32_e32 v2, v2
	v_exp_f32_e32 v3, v3
	v_add_f32_e32 v7, v7, v7
	v_mul_f32_e32 v7, 0x3fb8aa3b, v7
	v_exp_f32_e32 v89, v7
	v_add_f32_e32 v7, 1.0, v10
	v_add_f32_e32 v10, 1.0, v11
	v_add_f32_e32 v11, 1.0, v2
	v_add_f32_e32 v102, 1.0, v3
	v_rcp_f32_e32 v2, v7
	v_rcp_f32_e32 v3, v10
	v_mul_f32_e32 v108, 0x3d372713, v6
	v_lshlrev_b32_e32 v4, 16, v5
	v_and_b32_e32 v5, 0xffff0000, v5
	v_pk_fma_f32 v[2:3], v[2:3], 2.0, 1.0 op_sel_hi:[1,0,0] neg_lo:[1,0,0] neg_hi:[1,0,0]
	v_lshlrev_b32_e32 v8, 16, v9
	v_mul_f32_e32 v108, v6, v108
	v_pk_add_f32 v[2:3], v[2:3], 1.0 op_sel_hi:[1,0]
	v_and_b32_e32 v9, 0xffff0000, v9
	v_fma_f32 v6, v6, v108, v6
	v_pk_mul_f32 v[2:3], v[94:95], v[2:3]
	v_lshlrev_b32_e32 v94, 16, v103
	v_and_b32_e32 v95, 0xffff0000, v103
	v_pk_fma_f32 v[4:5], v[54:55], v[4:5], v[8:9]
	v_mul_f32_e32 v6, 0x3f4c422a, v6
	v_pk_add_f32 v[4:5], v[4:5], v[94:95]
	v_add_f32_e32 v6, v6, v6
	v_mul_f32_e32 v8, 0x3d372713, v4
	v_mul_f32_e32 v6, 0x3fb8aa3b, v6
	v_mul_f32_e32 v8, v4, v8
	v_exp_f32_e32 v6, v6
	v_fma_f32 v8, v4, v8, v4
	v_mul_f32_e32 v8, 0x3f4c422a, v8
	v_add_f32_e32 v8, v8, v8
	v_mul_f32_e32 v8, 0x3fb8aa3b, v8
	v_add_f32_e32 v106, 1.0, v6
	v_rcp_f32_e32 v6, v11
	v_add_f32_e32 v11, 1.0, v89
	v_exp_f32_e32 v89, v8
	v_pk_mul_f32 v[8:9], v[4:5], 0.5 op_sel_hi:[1,0]
	v_mul_f32_e32 v4, 0x3d372713, v5
	v_mul_f32_e32 v4, v5, v4
	v_fmac_f32_e32 v5, v5, v4
	v_mul_f32_e32 v4, 0x3f4c422a, v5
	v_add_f32_e32 v4, v4, v4
	v_mul_f32_e32 v4, 0x3fb8aa3b, v4
	v_exp_f32_e32 v5, v4
	v_add_f32_e32 v4, 1.0, v89
	v_rcp_f32_e32 v7, v102
	v_rcp_f32_e32 v10, v106
	v_add_f32_e32 v5, 1.0, v5
	v_rcp_f32_e32 v11, v11
	v_rcp_f32_e32 v4, v4
	v_rcp_f32_e32 v5, v5
	v_pk_fma_f32 v[6:7], v[6:7], 2.0, 1.0 op_sel_hi:[1,0,0] neg_lo:[1,0,0] neg_hi:[1,0,0]
	v_pk_fma_f32 v[10:11], v[10:11], 2.0, 1.0 op_sel_hi:[1,0,0] neg_lo:[1,0,0] neg_hi:[1,0,0]
	v_pk_add_f32 v[6:7], v[6:7], 1.0 op_sel_hi:[1,0]
	v_pk_fma_f32 v[4:5], v[4:5], 2.0, 1.0 op_sel_hi:[1,0,0] neg_lo:[1,0,0] neg_hi:[1,0,0]
	v_pk_add_f32 v[10:11], v[10:11], 1.0 op_sel_hi:[1,0]
	v_pk_add_f32 v[4:5], v[4:5], 1.0 op_sel_hi:[1,0]
	v_pk_mul_f32 v[6:7], v[100:101], v[6:7]
	v_pk_mul_f32 v[10:11], v[104:105], v[10:11]
	v_pk_mul_f32 v[8:9], v[8:9], v[4:5]
	v_cvt_pk_bf16_f32 v2, v2, v3
	v_cvt_pk_bf16_f32 v3, v6, v7
	v_cvt_pk_bf16_f32 v4, v10, v11
	v_cvt_pk_bf16_f32 v5, v8, v9
	global_store_dwordx4 v[0:1], v[2:5], off
	v_mov_b32_e32 v89, 0
	s_nop 0
	v_lshlrev_b32_e32 v4, 1, v74
	v_mov_b32_e32 v5, v96
	v_lshl_add_u64 v[0:1], v[92:93], 0, v[4:5]
	global_load_dwordx4 v[0:3], v[0:1], off
	v_cndmask_b32_e32 v5, v222, v223, vcc
	v_and_b32_e32 v6, v5, v68
	v_cmp_ne_u32_e32 vcc, 0, v6
	v_mov_b32_e32 v164, 0
	v_mov_b32_e32 v165, 0
	v_mov_b32_e32 v166, 0
	v_mov_b32_e32 v167, 0
	s_and_saveexec_b64 s[0:1], vcc
	global_load_dwordx4 v[164:167], v[90:91], off offset:-3840
	s_mov_b64 exec, s[0:1]
	v_mov_b32_e32 v123, 0
	v_mov_b32_e32 v122, 0
	v_mov_b32_e32 v125, 0
	v_mov_b32_e32 v124, 0
	v_mov_b32_e32 v134, 0
	v_mov_b32_e32 v133, 0
	s_mov_b64 s[0:1], 0x1f00
	v_cmp_ne_u32_e64 s[6:7], v6, v5
	v_lshl_add_u64 v[94:95], v[92:93], 0, s[0:1]
	v_mov_b32_e32 v5, v96
	v_lshl_add_u64 v[4:5], v[94:95], 0, v[4:5]
	v_mov_b32_e32 v136, 0
	v_mov_b32_e32 v135, 0
	v_mov_b32_e32 v168, 0
	v_mov_b32_e32 v169, 0
	v_mov_b32_e32 v170, 0
	v_mov_b32_e32 v171, 0
	s_and_saveexec_b64 s[0:1], s[6:7]
	global_load_dwordx4 v[168:171], v[4:5], off
	s_mov_b64 exec, s[0:1]
	v_mov_b32_e32 v138, 0
	v_mov_b32_e32 v137, 0
	v_mov_b32_e32 v140, 0
	v_mov_b32_e32 v139, 0
	v_mov_b32_e32 v141, 0
	v_mov_b32_e32 v142, 0
	v_lshlrev_b32_e32 v8, 1, v84
	v_mov_b32_e32 v9, v96
	v_lshl_add_u64 v[4:5], v[92:93], 0, v[8:9]
	global_load_dwordx4 v[4:7], v[4:5], off
	v_mov_b32_e32 v115, 0
	v_mov_b32_e32 v114, 0
	v_mov_b32_e32 v172, 0
	v_mov_b32_e32 v173, 0
	v_mov_b32_e32 v174, 0
	v_mov_b32_e32 v175, 0
	s_and_saveexec_b64 s[0:1], vcc
	global_load_dwordx4 v[172:175], v[90:91], off offset:-2816
	s_mov_b64 exec, s[0:1]
	v_mov_b32_e32 v117, 0
	v_mov_b32_e32 v116, 0
	v_mov_b32_e32 v119, 0
	v_mov_b32_e32 v118, 0
	v_mov_b32_e32 v121, 0
	v_mov_b32_e32 v120, 0
	v_mov_b32_e32 v9, v96
	v_lshl_add_u64 v[8:9], v[94:95], 0, v[8:9]
	v_mov_b32_e32 v144, 0
	v_mov_b32_e32 v143, 0
	v_mov_b32_e32 v176, 0
	v_mov_b32_e32 v177, 0
	v_mov_b32_e32 v178, 0
	v_mov_b32_e32 v179, 0
	s_and_saveexec_b64 s[0:1], s[6:7]
	global_load_dwordx4 v[176:179], v[8:9], off
	s_mov_b64 exec, s[0:1]
	v_mov_b32_e32 v146, 0
	v_mov_b32_e32 v145, 0
	v_mov_b32_e32 v149, 0
	v_mov_b32_e32 v148, 0
	v_mov_b32_e32 v147, 0
	v_mov_b32_e32 v150, 0
	v_lshlrev_b32_e32 v100, 1, v86
	v_mov_b32_e32 v101, v96
	v_lshl_add_u64 v[8:9], v[92:93], 0, v[100:101]
	global_load_dwordx4 v[8:11], v[8:9], off
	v_mov_b32_e32 v152, 0
	v_mov_b32_e32 v151, 0
	v_mov_b32_e32 v180, 0
	v_mov_b32_e32 v181, 0
	v_mov_b32_e32 v182, 0
	v_mov_b32_e32 v183, 0
	s_and_saveexec_b64 s[0:1], vcc
	global_load_dwordx4 v[180:183], v[90:91], off offset:-1792
	s_mov_b64 exec, s[0:1]
	v_mov_b32_e32 v105, 0
	v_mov_b32_e32 v104, 0
	v_mov_b32_e32 v109, 0
	v_mov_b32_e32 v108, 0
	v_mov_b32_e32 v113, 0
	v_mov_b32_e32 v112, 0
	v_mov_b32_e32 v101, v96
	v_lshl_add_u64 v[100:101], v[94:95], 0, v[100:101]
	v_mov_b32_e32 v155, 0
	v_mov_b32_e32 v154, 0
	v_mov_b32_e32 v184, 0
	v_mov_b32_e32 v185, 0
	v_mov_b32_e32 v186, 0
	v_mov_b32_e32 v187, 0
	s_and_saveexec_b64 s[0:1], s[6:7]
	global_load_dwordx4 v[184:187], v[100:101], off
	s_mov_b64 exec, s[0:1]
	v_mov_b32_e32 v103, 0
	v_mov_b32_e32 v102, 0
	v_mov_b32_e32 v107, 0
	v_mov_b32_e32 v106, 0
	v_mov_b32_e32 v153, 0
	v_mov_b32_e32 v110, 0
	v_lshlrev_b64 v[126:127], 9, v[98:99]
	s_waitcnt vmcnt(0)
	v_lshlrev_b32_e32 v98, 16, v184
	v_lshlrev_b32_e32 v154, 16, v177
	v_and_b32_e32 v145, 0xffff0000, v176
	v_lshlrev_b32_e32 v144, 16, v176
	v_and_b32_e32 v115, 0xffff0000, v172
	v_lshlrev_b32_e32 v114, 16, v172
	v_and_b32_e32 v159, 0xffff0000, v174
	v_lshlrev_b32_e32 v158, 16, v174
	v_lshlrev_b32_e32 v118, 16, v4
	v_and_b32_e32 v119, 0xffff0000, v4
	v_pk_add_f32 v[114:115], v[114:115], v[144:145]
	v_and_b32_e32 v99, 0xffff0000, v184
	v_and_b32_e32 v155, 0xffff0000, v177
	v_and_b32_e32 v117, 0xffff0000, v173
	v_lshlrev_b32_e32 v116, 16, v173
	v_pk_fma_f32 v[114:115], v[114:115], 0.5, v[118:119] op_sel_hi:[1,0,1] neg_lo:[0,0,1] neg_hi:[0,0,1]
	v_and_b32_e32 v157, 0xffff0000, v175
	v_lshlrev_b32_e32 v156, 16, v175
	v_lshlrev_b32_e32 v4, 16, v5
	v_and_b32_e32 v5, 0xffff0000, v5
	v_pk_fma_f32 v[120:121], v[22:23], v[114:115], v[118:119]
	v_pk_add_f32 v[114:115], v[116:117], v[154:155]
	v_and_b32_e32 v149, 0xffff0000, v178
	v_lshlrev_b32_e32 v148, 16, v178
	v_pk_fma_f32 v[114:115], v[114:115], 0.5, v[4:5] op_sel_hi:[1,0,1] neg_lo:[0,0,1] neg_hi:[0,0,1]
	v_lshlrev_b32_e32 v160, 16, v6
	v_and_b32_e32 v161, 0xffff0000, v6
	v_pk_fma_f32 v[118:119], v[36:37], v[114:115], v[4:5]
	v_pk_add_f32 v[4:5], v[158:159], v[148:149]
	v_lshlrev_b32_e32 v100, 16, v180
	v_lshlrev_b32_e32 v150, 16, v179
	v_and_b32_e32 v151, 0xffff0000, v179
	v_pk_fma_f32 v[4:5], v[4:5], 0.5, v[160:161] op_sel_hi:[1,0,1] neg_lo:[0,0,1] neg_hi:[0,0,1]
	v_lshlrev_b32_e32 v144, 16, v170
	v_and_b32_e32 v139, 0xffff0000, v169
	v_lshlrev_b32_e32 v138, 16, v169
	v_and_b32_e32 v137, 0xffff0000, v168
	v_lshlrev_b32_e32 v136, 16, v168
	v_and_b32_e32 v147, 0xffff0000, v166
	v_lshlrev_b32_e32 v146, 16, v166
	v_and_b32_e32 v125, 0xffff0000, v164
	v_lshlrev_b32_e32 v124, 16, v164
	v_pk_fma_f32 v[116:117], v[50:51], v[4:5], v[160:161]
	v_pk_add_f32 v[4:5], v[156:157], v[150:151]
	v_lshlrev_b32_e32 v148, 16, v0
	v_and_b32_e32 v149, 0xffff0000, v0
	v_lshlrev_b32_e32 v150, 16, v2
	v_and_b32_e32 v151, 0xffff0000, v2
	v_lshlrev_b32_e32 v154, 16, v3
	v_and_b32_e32 v155, 0xffff0000, v3
	v_pk_add_f32 v[2:3], v[124:125], v[136:137]
	v_and_b32_e32 v123, 0xffff0000, v165
	v_lshlrev_b32_e32 v122, 16, v165
	v_pk_fma_f32 v[2:3], v[2:3], 0.5, v[148:149] op_sel_hi:[1,0,1] neg_lo:[0,0,1] neg_hi:[0,0,1]
	v_lshlrev_b32_e32 v0, 16, v1
	v_and_b32_e32 v1, 0xffff0000, v1
	v_pk_fma_f32 v[124:125], v[20:21], v[2:3], v[148:149]
	v_pk_add_f32 v[2:3], v[122:123], v[138:139]
	v_and_b32_e32 v145, 0xffff0000, v170
	v_pk_fma_f32 v[2:3], v[2:3], 0.5, v[0:1] op_sel_hi:[1,0,1] neg_lo:[0,0,1] neg_hi:[0,0,1]
	v_lshlrev_b64 v[128:129], 9, v[68:69]
	v_pk_fma_f32 v[122:123], v[34:35], v[2:3], v[0:1]
	v_pk_add_f32 v[0:1], v[146:147], v[144:145]
	v_lshlrev_b32_e32 v142, 16, v171
	v_and_b32_e32 v135, 0xffff0000, v167
	v_lshlrev_b32_e32 v134, 16, v167
	v_and_b32_e32 v143, 0xffff0000, v171
	v_pk_fma_f32 v[0:1], v[0:1], 0.5, v[150:151] op_sel_hi:[1,0,1] neg_lo:[0,0,1] neg_hi:[0,0,1]
	v_lshlrev_b64 v[128:129], 1, v[128:129]
	v_pk_fma_f32 v[2:3], v[48:49], v[0:1], v[150:151]
	v_pk_add_f32 v[0:1], v[134:135], v[142:143]
	v_lshl_add_u64 v[134:135], v[76:77], 0, v[128:129]
	v_lshl_add_u64 v[126:127], v[126:127], 1, v[76:77]
	global_load_dwordx4 v[134:137], v[134:135], off
	v_pk_mul_f32 v[120:121], v[124:125], v[120:121]
	global_load_dwordx4 v[138:141], v[126:127], off
	v_pk_mul_f32 v[120:121], v[18:19], v[120:121]
	v_pk_mul_f32 v[118:119], v[122:123], v[118:119]
	v_add_f32_e32 v89, 0, v120
	v_lshlrev_b32_e32 v6, 16, v7
	v_and_b32_e32 v7, 0xffff0000, v7
	v_add_f32_e32 v89, v89, v121
	v_pk_mul_f32 v[118:119], v[32:33], v[118:119]
	v_and_b32_e32 v101, 0xffff0000, v180
	v_pk_fma_f32 v[4:5], v[4:5], 0.5, v[6:7] op_sel_hi:[1,0,1] neg_lo:[0,0,1] neg_hi:[0,0,1]
	v_pk_fma_f32 v[0:1], v[0:1], 0.5, v[154:155] op_sel_hi:[1,0,1] neg_lo:[0,0,1] neg_hi:[0,0,1]
	v_add_f32_e32 v89, v89, v118
	v_pk_mul_f32 v[2:3], v[2:3], v[116:117]
	v_pk_fma_f32 v[114:115], v[64:65], v[4:5], v[6:7]
	v_lshlrev_b32_e32 v4, 16, v8
	v_and_b32_e32 v5, 0xffff0000, v8
	v_pk_fma_f32 v[0:1], v[62:63], v[0:1], v[154:155]
	v_add_f32_e32 v89, v89, v119
	v_pk_mul_f32 v[2:3], v[46:47], v[2:3]
	v_pk_add_f32 v[98:99], v[100:101], v[98:99]
	v_and_b32_e32 v103, 0xffff0000, v185
	v_lshlrev_b32_e32 v102, 16, v185
	v_and_b32_e32 v105, 0xffff0000, v181
	v_lshlrev_b32_e32 v104, 16, v181
	v_add_f32_e32 v2, v89, v2
	v_pk_mul_f32 v[0:1], v[0:1], v[114:115]
	v_pk_fma_f32 v[98:99], v[98:99], 0.5, v[4:5] op_sel_hi:[1,0,1] neg_lo:[0,0,1] neg_hi:[0,0,1]
	v_lshlrev_b32_e32 v6, 16, v9
	v_and_b32_e32 v7, 0xffff0000, v9
	v_add_f32_e32 v2, v2, v3
	v_pk_mul_f32 v[0:1], v[60:61], v[0:1]
	v_pk_add_f32 v[102:103], v[104:105], v[102:103]
	v_pk_fma_f32 v[4:5], v[24:25], v[98:99], v[4:5]
	v_and_b32_e32 v107, 0xffff0000, v186
	v_lshlrev_b32_e32 v106, 16, v186
	v_and_b32_e32 v109, 0xffff0000, v182
	v_lshlrev_b32_e32 v108, 16, v182
	v_add_f32_e32 v0, v2, v0
	v_pk_fma_f32 v[102:103], v[102:103], 0.5, v[6:7] op_sel_hi:[1,0,1] neg_lo:[0,0,1] neg_hi:[0,0,1]
	v_lshlrev_b32_e32 v8, 16, v10
	v_and_b32_e32 v9, 0xffff0000, v10
	v_add_f32_e32 v0, v0, v1
	v_pk_add_f32 v[106:107], v[108:109], v[106:107]
	v_pk_fma_f32 v[6:7], v[38:39], v[102:103], v[6:7]
	v_lshlrev_b32_e32 v110, 16, v187
	v_and_b32_e32 v113, 0xffff0000, v183
	v_lshlrev_b32_e32 v112, 16, v183
	v_and_b32_e32 v111, 0xffff0000, v187
	v_pk_fma_f32 v[106:107], v[106:107], 0.5, v[8:9] op_sel_hi:[1,0,1] neg_lo:[0,0,1] neg_hi:[0,0,1]
	v_lshlrev_b32_e32 v10, 16, v11
	v_and_b32_e32 v11, 0xffff0000, v11
	v_pk_add_f32 v[2:3], v[112:113], v[110:111]
	v_pk_fma_f32 v[8:9], v[52:53], v[106:107], v[8:9]
	v_pk_fma_f32 v[2:3], v[2:3], 0.5, v[10:11] op_sel_hi:[1,0,1] neg_lo:[0,0,1] neg_hi:[0,0,1]
	v_add_f32_dpp v0, v0, v0 quad_perm:[1,0,3,2] row_mask:0xf bank_mask:0xf bound_ctrl:1
	v_pk_fma_f32 v[2:3], v[66:67], v[2:3], v[10:11]
	s_waitcnt vmcnt(1)
	v_lshlrev_b32_e32 v98, 16, v134
	v_and_b32_e32 v99, 0xffff0000, v134
	s_waitcnt vmcnt(0)
	v_lshlrev_b32_e32 v100, 16, v138
	v_and_b32_e32 v101, 0xffff0000, v138
	v_pk_add_f32 v[98:99], v[98:99], v[100:101]
	v_lshlrev_b32_e32 v102, 16, v135
	v_and_b32_e32 v103, 0xffff0000, v135
	v_lshlrev_b32_e32 v104, 16, v139
	v_and_b32_e32 v105, 0xffff0000, v139
	v_add_f32_e32 v1, 0, v98
	v_pk_add_f32 v[102:103], v[102:103], v[104:105]
	v_add_f32_e32 v1, v99, v1
	v_lshlrev_b32_e32 v106, 16, v136
	v_and_b32_e32 v107, 0xffff0000, v136
	v_lshlrev_b32_e32 v108, 16, v140
	v_and_b32_e32 v109, 0xffff0000, v140
	v_add_f32_e32 v1, v102, v1
	v_pk_add_f32 v[106:107], v[106:107], v[108:109]
	v_add_f32_e32 v1, v103, v1
	v_lshlrev_b32_e32 v10, 16, v137
	v_and_b32_e32 v11, 0xffff0000, v137
	v_lshlrev_b32_e32 v110, 16, v141
	v_and_b32_e32 v111, 0xffff0000, v141
	v_add_f32_e32 v1, v106, v1
	v_pk_add_f32 v[10:11], v[10:11], v[110:111]
	v_add_f32_e32 v1, v107, v1
	v_add_f32_e32 v1, v10, v1
	v_add_f32_e32 v1, v11, v1
	v_add_f32_dpp v0, v0, v0 quad_perm:[2,3,0,1] row_mask:0xf bank_mask:0xf bound_ctrl:1
	s_nop 0
	v_add_f32_dpp v1, v1, v1 quad_perm:[1,0,3,2] row_mask:0xf bank_mask:0xf bound_ctrl:1
	v_add_f32_dpp v0, v0, v0 row_half_mirror row_mask:0xf bank_mask:0xf bound_ctrl:1
	s_nop 0
	v_add_f32_dpp v1, v1, v1 quad_perm:[2,3,0,1] row_mask:0xf bank_mask:0xf bound_ctrl:1
	s_nop 1
	v_add_f32_dpp v1, v1, v1 row_half_mirror row_mask:0xf bank_mask:0xf bound_ctrl:1
	v_mul_f32_e32 v100, 0x3c800000, v1
	v_pk_add_f32 v[98:99], v[98:99], v[100:101] op_sel_hi:[1,0] neg_lo:[0,1] neg_hi:[0,1]
	v_pk_add_f32 v[102:103], v[102:103], v[100:101] op_sel_hi:[1,0] neg_lo:[0,1] neg_hi:[0,1]
	v_pk_mul_f32 v[104:105], v[98:99], v[98:99]
	v_pk_mul_f32 v[108:109], v[102:103], v[102:103]
	v_add_f32_e32 v1, v104, v105
	v_pk_add_f32 v[106:107], v[106:107], v[100:101] op_sel_hi:[1,0] neg_lo:[0,1] neg_hi:[0,1]
	v_add_f32_e32 v1, v108, v1
	v_pk_mul_f32 v[110:111], v[106:107], v[106:107]
	v_add_f32_e32 v1, v109, v1
	v_pk_add_f32 v[10:11], v[10:11], v[100:101] op_sel_hi:[1,0] neg_lo:[0,1] neg_hi:[0,1]
	v_add_f32_e32 v1, v110, v1
	v_pk_mul_f32 v[100:101], v[10:11], v[10:11]
	v_add_f32_e32 v1, v111, v1
	v_add_f32_e32 v1, v100, v1
	v_add_f32_e32 v1, v101, v1
	s_nop 1
	v_add_f32_dpp v1, v1, v1 quad_perm:[1,0,3,2] row_mask:0xf bank_mask:0xf bound_ctrl:1
	s_nop 1
	v_add_f32_dpp v1, v1, v1 quad_perm:[2,3,0,1] row_mask:0xf bank_mask:0xf bound_ctrl:1
	s_nop 1
	v_add_f32_dpp v1, v1, v1 row_half_mirror row_mask:0xf bank_mask:0xf bound_ctrl:1
	v_fmamk_f32 v1, v1, 0x3c800000, v210
	v_cmp_gt_f32_e64 s[0:1], s33, v1
	v_mul_f32_e32 v89, 0x4b800000, v1
	s_nop 0
	v_cndmask_b32_e64 v1, v1, v89, s[0:1]
	v_rsq_f32_e32 v1, v1
	s_nop 0
	v_mul_f32_e32 v89, 0x45800000, v1
	v_cndmask_b32_e64 v100, v1, v89, s[0:1]
	v_pk_mul_f32 v[98:99], v[98:99], v[100:101] op_sel_hi:[1,0]
	v_pk_mul_f32 v[10:11], v[10:11], v[100:101] op_sel_hi:[1,0]
	v_pk_fma_f32 v[98:99], v[14:15], v[98:99], v[16:17]
	v_pk_fma_f32 v[10:11], v[56:57], v[10:11], v[58:59]
	v_pk_fma_f32 v[4:5], v[4:5], v[0:1], v[98:99] op_sel_hi:[1,0,1]
	v_pk_mul_f32 v[98:99], v[102:103], v[100:101] op_sel_hi:[1,0]
	v_pk_fma_f32 v[10:11], v[2:3], v[0:1], v[10:11] op_sel_hi:[1,0,1]
	v_pk_fma_f32 v[98:99], v[28:29], v[98:99], v[30:31]
	v_cvt_pk_bf16_f32 v3, v10, v11
	v_pk_fma_f32 v[6:7], v[6:7], v[0:1], v[98:99] op_sel_hi:[1,0,1]
	v_pk_mul_f32 v[98:99], v[106:107], v[100:101] op_sel_hi:[1,0]
	s_nop 0
	v_pk_fma_f32 v[98:99], v[42:43], v[98:99], v[44:45]
	s_nop 0
	v_pk_fma_f32 v[8:9], v[8:9], v[0:1], v[98:99] op_sel_hi:[1,0,1]
	v_cvt_pk_bf16_f32 v0, v4, v5
	v_cvt_pk_bf16_f32 v1, v6, v7
	v_cvt_pk_bf16_f32 v2, v8, v9
	v_lshl_add_u64 v[4:5], v[78:79], 0, v[128:129]
	global_store_dwordx4 v[4:5], v[0:3], off
	s_and_saveexec_b64 s[0:1], s[4:5]
	s_cbranch_execz .LBB0_561
	v_lshlrev_b32_e32 v8, 1, v80
	v_mov_b32_e32 v9, v96
	v_lshl_add_u64 v[0:1], v[92:93], 0, v[8:9]
	global_load_dwordx4 v[0:3], v[0:1], off
	v_mov_b32_e32 v164, 0
	v_mov_b32_e32 v165, 0
	v_mov_b32_e32 v166, 0
	v_mov_b32_e32 v167, 0
	v_mov_b32_e32 v168, 0
	v_mov_b32_e32 v169, 0
	v_mov_b32_e32 v170, 0
	v_mov_b32_e32 v171, 0
	s_and_saveexec_b64 s[12:13], vcc
	global_load_dwordx4 v[164:167], v[90:91], off offset:-256
	s_mov_b64 exec, s[12:13]
	v_mov_b32_e32 v9, v96
	v_lshl_add_u64 v[10:11], v[94:95], 0, v[8:9]
	s_and_saveexec_b64 s[12:13], s[6:7]
	global_load_dwordx4 v[168:171], v[10:11], off
	s_mov_b64 exec, s[12:13]
	s_waitcnt vmcnt(0)
	v_lshlrev_b32_e32 v98, 16, v164
	v_and_b32_e32 v93, 0xffff0000, v164
	v_lshlrev_b32_e32 v4, 16, v165
	v_mov_b32_e32 v5, v165
	v_lshlrev_b32_e32 v89, 16, v166
	v_mov_b32_e32 v99, v166
	v_lshlrev_b32_e32 v92, 16, v167
	v_mov_b32_e32 v100, v167
	v_lshlrev_b32_e32 v91, 16, v168
	v_and_b32_e32 v90, 0xffff0000, v168
	v_lshlrev_b32_e32 v6, 16, v169
	v_mov_b32_e32 v7, v169
	v_lshlrev_b32_e32 v9, 16, v170
	v_mov_b32_e32 v95, v170
	v_lshlrev_b32_e32 v8, 16, v171
	v_mov_b32_e32 v94, v171
	s_mov_b64 s[12:13], exec
	s_branch .LBB0_560
